# v37: v35 + two-k-step-deep operand prefetch (two register sets, parity select) in both prompt-item loops of the P2 pre-pass
# baseline (speedup 1.0000x reference)
.LBB0_591:
	v_add_u32_e32 v52, s12, v61
	s_mov_b64 s[0:1], -1
	s_and_b64 vcc, exec, s[40:41]
	v_lshlrev_b32_e32 v50, 1, v60
	s_cbranch_vccz .LBB0_600
	s_lshl_b32 s0, s16, 7
	v_mov_b64_e32 v[2:3], s[58:59]
	s_add_i32 s40, s0, 0xfffffe00
	v_mad_i64_i32 v[2:3], s[0:1], v52, s89, v[2:3]
	s_mov_b32 s41, s61
	v_lshl_add_u64 v[2:3], s[40:41], 1, v[2:3]
	v_mov_b32_e32 v51, v57
	v_lshl_add_u64 v[38:39], v[2:3], 0, v[50:51]
	v_add_co_u32_e32 v2, vcc, 0x1000, v38
	s_mov_b64 s[0:1], 0x1000
	s_nop 0
	v_addc_co_u32_e32 v3, vcc, 0, v39, vcc
	global_load_dwordx4 v[22:25], v[2:3], off
	global_load_dwordx4 v[18:21], v[38:39], off offset:3072
	v_mov_b32_e32 v2, 0
	s_mov_b32 s17, 0
	s_mov_b32 s42, 16
	v_lshl_add_u32 v51, s16, 9, v182
	v_mov_b32_e32 v53, v63
	v_mov_b32_e32 v56, v184
	v_mov_b32_e32 v3, v2
	v_mov_b32_e32 v4, v2
	v_mov_b32_e32 v5, v2
	v_mov_b32_e32 v6, v2
	v_mov_b32_e32 v7, v2
	v_mov_b32_e32 v8, v2
	v_mov_b32_e32 v9, v2
	v_mov_b32_e32 v10, v2
	v_mov_b32_e32 v11, v2
	v_mov_b32_e32 v12, v2
	v_mov_b32_e32 v13, v2
	v_mov_b32_e32 v14, v2
	v_mov_b32_e32 v15, v2
	v_mov_b32_e32 v16, v2
	v_lshl_add_u64 v[40:41], v[38:39], 0, s[0:1]
	v_mov_b32_e32 v17, v2
	s_waitcnt vmcnt(1)
	v_lshlrev_b32_e32 v30, 16, v22
	v_and_b32_e32 v31, 0xffff0000, v22
	v_lshlrev_b32_e32 v32, 16, v23
	v_and_b32_e32 v33, 0xffff0000, v23
	v_lshlrev_b32_e32 v75, 16, v24
	v_and_b32_e32 v77, 0xffff0000, v24
	v_lshlrev_b32_e32 v71, 16, v25
	v_and_b32_e32 v73, 0xffff0000, v25
	s_mov_b32 s99, 0
	v_lshl_add_u64 v[240:241], v[38:39], 0, 32
	v_lshl_add_u64 v[242:243], v[40:41], 0, 32
	global_load_dwordx4 v[232:235], v[240:241], off offset:3072
	global_load_dwordx4 v[236:239], v[242:243], off
	s_branch .LBB0_594
.LBB0_593:
	s_or_b64 exec, exec, s[0:1]
	s_add_i32 s17, s17, 64
	s_add_i32 s42, s42, 16
	s_waitcnt vmcnt(2)
	s_xor_b32 s99, s99, 1
	s_cmp_eq_u32 s99, 0
	s_cbranch_scc0 .Lp2hB_botB
	v_lshlrev_b32_e32 v30, 16, v22
	v_and_b32_e32 v31, 0xffff0000, v22
	v_lshlrev_b32_e32 v32, 16, v23
	v_and_b32_e32 v33, 0xffff0000, v23
	v_lshlrev_b32_e32 v75, 16, v24
	v_and_b32_e32 v77, 0xffff0000, v24
	v_lshlrev_b32_e32 v71, 16, v25
	v_and_b32_e32 v73, 0xffff0000, v25
	s_branch .Lp2hB_botE
.Lp2hB_botB:
	v_lshlrev_b32_e32 v30, 16, v236
	v_and_b32_e32 v31, 0xffff0000, v236
	v_lshlrev_b32_e32 v32, 16, v237
	v_and_b32_e32 v33, 0xffff0000, v237
	v_lshlrev_b32_e32 v75, 16, v238
	v_and_b32_e32 v77, 0xffff0000, v238
	v_lshlrev_b32_e32 v71, 16, v239
	v_and_b32_e32 v73, 0xffff0000, v239
.Lp2hB_botE:
	v_add_u32_e32 v56, 0x400, v56
	s_cmpk_eq_i32 s17, 0x200
	v_add_u32_e32 v53, 2, v53
	s_cbranch_scc1 .Lp2hB_exit
.LBB0_594:
	v_mul_f32_e64 v42, |v30|, s80
	v_exp_f32_e32 v42, v42
	v_mul_f32_e64 v43, |v31|, s80
	v_exp_f32_e32 v43, v43
	s_add_i32 s60, s42, 16
	s_min_u32 s60, s60, 0x70
	v_add_f32_e32 v46, 1.0, v42
	s_lshl_b64 s[0:1], s[60:61], 1
	v_lshl_add_u64 v[240:241], v[38:39], 0, s[0:1]
	v_lshl_add_u64 v[242:243], v[40:41], 0, s[0:1]
	s_waitcnt vmcnt(2)
	s_cmp_eq_u32 s99, 0
	s_cbranch_scc0 .Lp2hB_topB
	v_mov_b64_e32 v[28:29], v[20:21]
	v_mov_b64_e32 v[26:27], v[18:19]
	global_load_dwordx4 v[18:21], v[240:241], off offset:3072
	global_load_dwordx4 v[22:25], v[242:243], off
	s_branch .Lp2hB_mid
.Lp2hB_topB:
	v_mov_b64_e32 v[28:29], v[234:235]
	v_mov_b64_e32 v[26:27], v[232:233]
	global_load_dwordx4 v[232:235], v[240:241], off offset:3072
	global_load_dwordx4 v[236:239], v[242:243], off
.Lp2hB_mid:
	v_rcp_f32_e32 v48, v46
	v_add_f32_e32 v46, 1.0, v43
	v_add_u32_e32 v34, s17, v51
	v_rcp_f32_e32 v49, v46
	v_cmp_nle_f32_e64 s[0:1], 0, v30
	ds_read_b128 v[80:83], v34
	ds_read_b128 v[34:37], v34 offset:16
	v_pk_mul_f32 v[42:43], v[42:43], v[48:49]
	v_cmp_nle_f32_e32 vcc, 0, v31
	v_cndmask_b32_e64 v79, v48, v42, s[0:1]
	s_waitcnt lgkmcnt(1)
	v_pk_add_f32 v[30:31], v[80:81], 1.0 op_sel_hi:[1,0] neg_lo:[1,0] neg_hi:[1,0]
	v_cndmask_b32_e64 v42, v42, v48, s[0:1]
	v_fma_f32 v79, v30, v79, v80
	v_cndmask_b32_e32 v80, v49, v43, vcc
	v_cndmask_b32_e32 v43, v43, v49, vcc
	v_fma_f32 v48, v31, v80, v81
	v_pk_mul_f32 v[42:43], v[30:31], v[42:43]
	v_mul_f32_e64 v44, |v32|, s80
	v_mov_b32_e32 v30, v79
	s_nop 1
	v_mul_f32_dpp v30, v30, v30 row_shr:1 row_mask:0xf bank_mask:0xf
	v_mov_b32_e32 v31, v48
	s_nop 1
	v_mul_f32_dpp v31, v31, v31 row_shr:1 row_mask:0xf bank_mask:0xf
	v_exp_f32_e32 v54, v44
	v_mul_f32_e64 v44, |v33|, s80
	v_mul_f32_dpp v30, v30, v30 row_shr:2 row_mask:0xf bank_mask:0xf
	v_exp_f32_e32 v55, v44
	v_add_f32_e32 v46, 1.0, v54
	v_mul_f32_dpp v31, v31, v31 row_shr:2 row_mask:0xf bank_mask:0xf
	v_rcp_f32_e32 v86, v46
	v_add_f32_e32 v46, 1.0, v55
	v_mul_f32_dpp v30, v30, v30 row_shr:4 row_mask:0xf bank_mask:0xf
	v_rcp_f32_e32 v87, v46
	v_cmp_nle_f32_e32 vcc, 0, v33
	v_mul_f32_dpp v31, v31, v31 row_shr:4 row_mask:0xf bank_mask:0xf
	v_pk_mul_f32 v[54:55], v[54:55], v[86:87]
	v_mul_f32_e64 v44, |v75|, s80
	v_mul_f32_dpp v30, v30, v30 row_shr:8 row_mask:0xf bank_mask:0xf
	v_exp_f32_e32 v84, v44
	v_mul_f32_e64 v44, |v77|, s80
	v_mul_f32_dpp v31, v31, v31 row_shr:8 row_mask:0xf bank_mask:0xf
	v_exp_f32_e32 v85, v44
	v_add_f32_e32 v46, 1.0, v84
	v_mul_f32_dpp v30, v30, v30 row_bcast:15 row_mask:0xa bank_mask:0xf
	v_rcp_f32_e32 v88, v46
	v_add_f32_e32 v46, 1.0, v85
	v_mul_f32_dpp v31, v31, v31 row_bcast:15 row_mask:0xa bank_mask:0xf
	v_max_f32_e32 v48, 0x554ad2e, v30
	v_max_f32_e32 v49, 0x554ad2e, v31
	v_rcp_f32_e32 v80, v48
	v_rcp_f32_e32 v81, v49
	v_readlane_b32 s0, v48, 31
	v_readlane_b32 s1, v48, 63
	v_rcp_f32_e32 v89, v46
	v_pk_mul_f32 v[42:43], v[42:43], v[80:81]
	v_lshlrev_b32_e32 v80, 16, v26
	v_and_b32_e32 v81, 0xffff0000, v26
	v_mul_f32_e32 v26, 0xbfb8aa3b, v80
	v_exp_f32_e32 v26, v26
	v_mul_f32_e32 v90, 0xbfb8aa3b, v81
	v_exp_f32_e32 v91, v90
	v_mov_b32_e32 v30, s1
	v_add_f32_e32 v26, 1.0, v26
	v_rcp_f32_e32 v90, v26
	v_add_f32_e32 v26, 1.0, v91
	v_rcp_f32_e32 v91, v26
	v_mov_b32_e32 v31, s0
	v_readlane_b32 s0, v49, 31
	v_readlane_b32 s1, v49, 63
	v_cndmask_b32_e64 v30, v30, v31, s[2:3]
	v_mov_b32_e32 v79, s0
	v_mov_b32_e32 v31, s1
	v_pk_mul_f32 v[80:81], v[90:91], v[80:81]
	v_cmp_nle_f32_e64 s[0:1], 0, v32
	v_pk_mul_f32 v[48:49], v[80:81], v[48:49]
	v_pk_add_f32 v[32:33], v[82:83], 1.0 op_sel_hi:[1,0] neg_lo:[1,0] neg_hi:[1,0]
	v_cndmask_b32_e64 v26, v86, v54, s[0:1]
	v_cndmask_b32_e32 v80, v87, v55, vcc
	v_cndmask_b32_e32 v55, v55, v87, vcc
	v_cndmask_b32_e64 v54, v54, v86, s[0:1]
	v_fma_f32 v26, v32, v26, v82
	v_pk_mul_f32 v[54:55], v[32:33], v[54:55]
	v_fmac_f32_e32 v83, v33, v80
	v_mul_f32_dpp v26, v26, v26 row_shr:1 row_mask:0xf bank_mask:0xf
	v_cmp_nle_f32_e32 vcc, 0, v77
	v_mov_b32_e32 v32, v83
	s_nop 1
	v_mul_f32_dpp v32, v32, v32 row_shr:1 row_mask:0xf bank_mask:0xf
	v_mul_f32_dpp v26, v26, v26 row_shr:2 row_mask:0xf bank_mask:0xf
	v_mul_f32_e64 v44, |v71|, s80
	v_mul_f32_e64 v45, |v73|, s80
	v_mul_f32_dpp v32, v32, v32 row_shr:2 row_mask:0xf bank_mask:0xf
	v_exp_f32_e32 v44, v44
	v_exp_f32_e32 v45, v45
	v_mul_f32_dpp v26, v26, v26 row_shr:4 row_mask:0xf bank_mask:0xf
	v_add_f32_e32 v46, 1.0, v44
	v_add_f32_e32 v47, 1.0, v45
	v_mul_f32_dpp v32, v32, v32 row_shr:4 row_mask:0xf bank_mask:0xf
	v_rcp_f32_e32 v46, v46
	v_rcp_f32_e32 v47, v47
	v_mul_f32_dpp v26, v26, v26 row_shr:8 row_mask:0xf bank_mask:0xf
	v_cndmask_b32_e64 v31, v31, v79, s[2:3]
	v_mul_f32_e32 v79, v42, v30
	v_mul_f32_dpp v32, v32, v32 row_shr:8 row_mask:0xf bank_mask:0xf
	v_mul_f32_e32 v90, v43, v31
	v_cvt_pk_bf16_f32 v42, v42, v43
	v_mul_f32_dpp v26, v26, v26 row_bcast:15 row_mask:0xa bank_mask:0xf
	v_max_f32_e32 v80, 0x554ad2e, v26
	v_rcp_f32_e32 v82, v80
	v_mul_f32_dpp v32, v32, v32 row_bcast:15 row_mask:0xa bank_mask:0xf
	v_max_f32_e32 v81, 0x554ad2e, v32
	v_rcp_f32_e32 v83, v81
	v_readlane_b32 s0, v80, 31
	v_readlane_b32 s1, v80, 63
	v_pk_mul_f32 v[54:55], v[54:55], v[82:83]
	s_nop 0
	v_mov_b32_e32 v26, s1
	v_mov_b32_e32 v32, s0
	v_readlane_b32 s0, v81, 31
	v_readlane_b32 s1, v81, 63
	v_cndmask_b32_e64 v32, v26, v32, s[2:3]
	v_mov_b32_e32 v33, s0
	v_mov_b32_e32 v26, s1
	v_cndmask_b32_e64 v33, v26, v33, s[2:3]
	v_lshlrev_b32_e32 v26, 16, v27
	v_and_b32_e32 v27, 0xffff0000, v27
	v_mul_f32_e32 v82, 0xbfb8aa3b, v26
	v_mul_f32_e32 v83, 0xbfb8aa3b, v27
	v_exp_f32_e32 v82, v82
	v_exp_f32_e32 v83, v83
	v_cmp_nle_f32_e64 s[0:1], 0, v75
	v_cvt_pk_bf16_f32 v43, v54, v55
	v_add_f32_e32 v82, 1.0, v82
	v_add_f32_e32 v83, 1.0, v83
	v_rcp_f32_e32 v82, v82
	v_rcp_f32_e32 v83, v83
	v_mul_f32_e32 v91, v54, v32
	v_mul_f32_e32 v92, v55, v33
	v_pk_mul_f32 v[26:27], v[82:83], v[26:27]
	v_pk_mul_f32 v[80:81], v[26:27], v[80:81]
	v_pk_mul_f32 v[26:27], v[84:85], v[88:89]
	s_waitcnt lgkmcnt(0)
	v_pk_add_f32 v[82:83], v[34:35], 1.0 op_sel_hi:[1,0] neg_lo:[1,0] neg_hi:[1,0]
	v_cndmask_b32_e64 v75, v88, v26, s[0:1]
	v_fma_f32 v34, v82, v75, v34
	v_cndmask_b32_e32 v75, v89, v27, vcc
	v_fma_f32 v35, v83, v75, v35
	v_cndmask_b32_e32 v27, v27, v89, vcc
	v_cndmask_b32_e64 v26, v26, v88, s[0:1]
	v_mul_f32_dpp v34, v34, v34 row_shr:1 row_mask:0xf bank_mask:0xf
	v_pk_mul_f32 v[26:27], v[82:83], v[26:27]
	v_cmp_nle_f32_e32 vcc, 0, v73
	v_mul_f32_dpp v35, v35, v35 row_shr:1 row_mask:0xf bank_mask:0xf
	v_mul_f32_dpp v34, v34, v34 row_shr:2 row_mask:0xf bank_mask:0xf
	s_nop 0
	v_mul_f32_dpp v35, v35, v35 row_shr:2 row_mask:0xf bank_mask:0xf
	v_mul_f32_dpp v34, v34, v34 row_shr:4 row_mask:0xf bank_mask:0xf
	s_nop 0
	v_mul_f32_dpp v35, v35, v35 row_shr:4 row_mask:0xf bank_mask:0xf
	v_mul_f32_dpp v34, v34, v34 row_shr:8 row_mask:0xf bank_mask:0xf
	s_nop 0
	v_mul_f32_dpp v35, v35, v35 row_shr:8 row_mask:0xf bank_mask:0xf
	v_mul_f32_dpp v34, v34, v34 row_bcast:15 row_mask:0xa bank_mask:0xf
	v_max_f32_e32 v82, 0x554ad2e, v34
	v_rcp_f32_e32 v84, v82
	v_mul_f32_dpp v35, v35, v35 row_bcast:15 row_mask:0xa bank_mask:0xf
	v_max_f32_e32 v83, 0x554ad2e, v35
	v_rcp_f32_e32 v85, v83
	v_readlane_b32 s0, v82, 31
	v_readlane_b32 s1, v82, 63
	v_pk_mul_f32 v[84:85], v[26:27], v[84:85]
	v_lshlrev_b32_e32 v26, 16, v28
	v_and_b32_e32 v27, 0xffff0000, v28
	v_mul_f32_e32 v28, 0xbfb8aa3b, v26
	v_exp_f32_e32 v28, v28
	v_mul_f32_e32 v77, 0xbfb8aa3b, v27
	v_exp_f32_e32 v77, v77
	v_mov_b32_e32 v34, s1
	v_add_f32_e32 v28, 1.0, v28
	v_rcp_f32_e32 v86, v28
	v_add_f32_e32 v28, 1.0, v77
	v_rcp_f32_e32 v87, v28
	v_mov_b32_e32 v35, s0
	v_readlane_b32 s0, v83, 31
	v_readlane_b32 s1, v83, 63
	v_pk_mul_f32 v[26:27], v[86:87], v[26:27]
	v_cndmask_b32_e64 v34, v34, v35, s[2:3]
	v_mov_b32_e32 v35, s1
	v_mov_b32_e32 v75, s0
	v_pk_mul_f32 v[82:83], v[26:27], v[82:83]
	v_pk_mul_f32 v[26:27], v[44:45], v[46:47]
	v_cmp_nle_f32_e64 s[0:1], 0, v71
	v_pk_add_f32 v[44:45], v[36:37], 1.0 op_sel_hi:[1,0] neg_lo:[1,0] neg_hi:[1,0]
	v_cndmask_b32_e64 v35, v35, v75, s[2:3]
	v_cndmask_b32_e64 v28, v46, v26, s[0:1]
	v_fma_f32 v28, v44, v28, v36
	v_cndmask_b32_e32 v36, v47, v27, vcc
	v_fmac_f32_e32 v37, v45, v36
	v_cndmask_b32_e32 v27, v27, v47, vcc
	v_cndmask_b32_e64 v26, v26, v46, s[0:1]
	v_mul_f32_dpp v28, v28, v28 row_shr:1 row_mask:0xf bank_mask:0xf
	v_pk_mul_f32 v[26:27], v[44:45], v[26:27]
	v_mul_f32_e32 v75, v84, v34
	v_mov_b32_e32 v36, v37
	s_nop 1
	v_mul_f32_dpp v36, v36, v36 row_shr:1 row_mask:0xf bank_mask:0xf
	v_mul_f32_e32 v77, v85, v35
	v_mul_f32_dpp v28, v28, v28 row_shr:2 row_mask:0xf bank_mask:0xf
	v_mul_f32_dpp v36, v36, v36 row_shr:2 row_mask:0xf bank_mask:0xf
	s_nop 0
	v_mul_f32_dpp v28, v28, v28 row_shr:4 row_mask:0xf bank_mask:0xf
	v_mul_f32_dpp v36, v36, v36 row_shr:4 row_mask:0xf bank_mask:0xf
	s_nop 0
	v_mul_f32_dpp v28, v28, v28 row_shr:8 row_mask:0xf bank_mask:0xf
	v_mul_f32_dpp v36, v36, v36 row_shr:8 row_mask:0xf bank_mask:0xf
	s_nop 0
	v_mul_f32_dpp v28, v28, v28 row_bcast:15 row_mask:0xa bank_mask:0xf
	v_max_f32_e32 v44, 0x554ad2e, v28
	v_rcp_f32_e32 v46, v44
	v_mul_f32_dpp v36, v36, v36 row_bcast:15 row_mask:0xa bank_mask:0xf
	v_max_f32_e32 v45, 0x554ad2e, v36
	v_rcp_f32_e32 v47, v45
	v_readlane_b32 s0, v44, 31
	v_readlane_b32 s1, v44, 63
	v_pk_mul_f32 v[46:47], v[26:27], v[46:47]
	s_nop 0
	v_mov_b32_e32 v28, s1
	v_mov_b32_e32 v36, s0
	v_readlane_b32 s0, v45, 31
	v_readlane_b32 s1, v45, 63
	v_cndmask_b32_e64 v36, v28, v36, s[2:3]
	v_mov_b32_e32 v37, s0
	v_mov_b32_e32 v28, s1
	v_lshlrev_b32_e32 v26, 16, v29
	v_and_b32_e32 v27, 0xffff0000, v29
	v_cndmask_b32_e64 v37, v28, v37, s[2:3]
	v_mul_f32_e32 v28, 0xbfb8aa3b, v26
	v_mul_f32_e32 v29, 0xbfb8aa3b, v27
	v_exp_f32_e32 v28, v28
	v_exp_f32_e32 v29, v29
	v_mul_f32_e32 v71, v46, v36
	v_mul_f32_e32 v73, v47, v37
	v_add_f32_e32 v28, 1.0, v28
	v_add_f32_e32 v29, 1.0, v29
	v_rcp_f32_e32 v28, v28
	v_rcp_f32_e32 v29, v29
	s_nop 0
	v_pk_mul_f32 v[26:27], v[28:29], v[26:27]
	v_pk_mul_f32 v[44:45], v[26:27], v[44:45]
	v_cvt_pk_bf16_f32 v26, v48, v49
	v_cvt_pk_bf16_f32 v29, v44, v45
	v_cvt_pk_bf16_f32 v44, v84, v85
	v_cvt_pk_bf16_f32 v45, v46, v47
	v_cvt_pk_bf16_f32 v27, v80, v81
	v_cvt_pk_bf16_f32 v28, v82, v83
	v_xor_b32_e32 v46, v53, v65
	v_lshl_add_u32 v46, v46, 4, v148
	v_mfma_f32_32x32x16_bf16 v[2:17], v[42:45], v[26:29], v[2:17]
	ds_write_b128 v46, v[26:29] offset:20480
	v_cvt_pk_bf16_f32 v46, v79, v90
	ds_write_b16 v56, v46
	ds_write_b16_d16_hi v56, v46 offset:64
	v_cvt_pk_bf16_f32 v46, v91, v92
	ds_write_b16 v56, v46 offset:128
	ds_write_b16_d16_hi v56, v46 offset:192
	v_cvt_pk_bf16_f32 v46, v75, v77
	ds_write_b16 v56, v46 offset:256
	ds_write_b16_d16_hi v56, v46 offset:320
	v_cvt_pk_bf16_f32 v46, v71, v73
	ds_write_b16 v56, v46 offset:384
	ds_write_b16_d16_hi v56, v46 offset:448
	s_and_saveexec_b64 s[0:1], s[4:5]
	s_cbranch_execz .LBB0_593
	v_add_u32_e32 v26, s17, v183
	ds_write_b128 v26, v[30:33]
	ds_write_b128 v26, v[34:37] offset:16
	s_branch .LBB0_593

.LBB0_630:
	v_ashrrev_i32_e32 v53, 31, v52
	v_readlane_b32 s0, v255, 19
	v_lshlrev_b64 v[2:3], 6, v[52:53]
	v_readlane_b32 s1, v255, 20
	s_lshl_b32 s40, s16, 7
	s_mov_b32 s41, s61
	v_lshl_add_u64 v[2:3], s[0:1], 0, v[2:3]
	global_load_dwordx4 v[16:19], v[2:3], off offset:48
	global_load_dwordx4 v[20:23], v[2:3], off offset:32
	global_load_dwordx4 v[24:27], v[2:3], off offset:16
	global_load_dwordx4 v[28:31], v[2:3], off
	v_mov_b64_e32 v[2:3], s[58:59]
	v_mad_i64_i32 v[2:3], s[0:1], v52, s89, v[2:3]
	v_lshl_add_u64 v[2:3], v[2:3], 0, s[40:41]
	v_mov_b32_e32 v51, v57
	v_lshl_add_u64 v[80:81], v[2:3], 0, v[50:51]
	global_load_dwordx4 v[32:35], v[80:81], off
	global_load_dwordx4 v[36:39], v[80:81], off offset:512
	v_mov_b32_e32 v2, 0
	s_lshl_b32 s17, s16, 6
	v_lshl_add_u32 v56, s16, 8, v59
	s_mov_b32 s41, 0
	s_mov_b32 s42, 16
	v_mov_b32_e32 v71, v63
	v_mov_b32_e32 v73, v184
	v_mov_b32_e32 v3, v2
	v_mov_b32_e32 v4, v2
	v_mov_b32_e32 v5, v2
	v_mov_b32_e32 v6, v2
	v_mov_b32_e32 v7, v2
	v_mov_b32_e32 v8, v2
	v_mov_b32_e32 v9, v2
	v_mov_b32_e32 v10, v2
	v_mov_b32_e32 v11, v2
	v_mov_b32_e32 v12, v2
	v_mov_b32_e32 v13, v2
	v_mov_b32_e32 v14, v2
	v_mov_b32_e32 v15, v2
	s_waitcnt vmcnt(5)
	v_mov_b32_e32 v118, v16
	s_waitcnt vmcnt(4)
	v_mov_b32_e32 v106, v20
	s_waitcnt vmcnt(3)
	v_mov_b32_e32 v94, v24
	s_waitcnt vmcnt(2)
	v_mov_b32_e32 v82, v28
	v_mov_b32_e32 v83, v28
	v_mov_b32_e32 v84, v28
	v_mov_b32_e32 v85, v28
	v_mov_b32_e32 v86, v29
	v_mov_b32_e32 v87, v29
	v_mov_b32_e32 v28, v29
	v_mov_b32_e32 v88, v30
	v_mov_b32_e32 v89, v30
	v_mov_b32_e32 v90, v30
	v_mov_b32_e32 v91, v30
	v_mov_b32_e32 v92, v31
	v_mov_b32_e32 v93, v31
	v_mov_b32_e32 v30, v31
	v_mov_b32_e32 v95, v24
	v_mov_b32_e32 v96, v24
	v_mov_b32_e32 v97, v24
	v_mov_b32_e32 v98, v25
	v_mov_b32_e32 v99, v25
	v_mov_b32_e32 v24, v25
	v_mov_b32_e32 v100, v26
	v_mov_b32_e32 v101, v26
	v_mov_b32_e32 v102, v26
	v_mov_b32_e32 v103, v26
	v_mov_b32_e32 v104, v27
	v_mov_b32_e32 v105, v27
	v_mov_b32_e32 v26, v27
	v_mov_b32_e32 v107, v20
	v_mov_b32_e32 v108, v20
	v_mov_b32_e32 v109, v20
	v_mov_b32_e32 v110, v21
	v_mov_b32_e32 v111, v21
	v_mov_b32_e32 v20, v21
	v_mov_b32_e32 v112, v22
	v_mov_b32_e32 v113, v22
	v_mov_b32_e32 v114, v22
	v_mov_b32_e32 v115, v22
	v_mov_b32_e32 v116, v23
	v_mov_b32_e32 v117, v23
	v_mov_b32_e32 v22, v23
	v_mov_b32_e32 v119, v16
	v_mov_b32_e32 v120, v16
	v_mov_b32_e32 v121, v16
	v_mov_b32_e32 v122, v17
	v_mov_b32_e32 v123, v17
	v_mov_b32_e32 v124, v17
	v_mov_b32_e32 v125, v17
	v_mov_b32_e32 v126, v18
	v_mov_b32_e32 v127, v18
	v_mov_b32_e32 v128, v18
	v_mov_b32_e32 v129, v18
	v_mov_b32_e32 v130, v19
	v_mov_b32_e32 v131, v19
	v_mov_b32_e32 v18, v19
	v_mov_b32_e32 v16, v2
	v_mov_b32_e32 v17, v2
	s_mov_b32 s99, 0
	v_lshl_add_u64 v[240:241], v[80:81], 0, 32
	global_load_dwordx4 v[232:235], v[240:241], off
	global_load_dwordx4 v[236:239], v[240:241], off offset:512
	s_branch .LBB0_632

.LBB0_632:
	s_add_i32 s60, s42, 16
	s_min_u32 s60, s60, 48
	v_lshl_add_u64 v[240:241], s[60:61], 1, v[80:81]
	v_add_u32_e32 v75, s41, v56
	s_waitcnt vmcnt(2)
	s_cmp_eq_u32 s99, 0
	s_cbranch_scc0 .Lp2gB_topB
	v_mov_b64_e32 v[42:43], v[38:39]
	v_mov_b64_e32 v[40:41], v[36:37]
	v_mov_b64_e32 v[46:47], v[34:35]
	v_mov_b64_e32 v[44:45], v[32:33]
	global_load_dwordx4 v[32:35], v[240:241], off
	global_load_dwordx4 v[36:39], v[240:241], off offset:512
	s_branch .Lp2gB_mid
.Lp2gB_topB:
	v_mov_b64_e32 v[42:43], v[238:239]
	v_mov_b64_e32 v[40:41], v[236:237]
	v_mov_b64_e32 v[46:47], v[234:235]
	v_mov_b64_e32 v[44:45], v[232:233]
	global_load_dwordx4 v[232:235], v[240:241], off
	global_load_dwordx4 v[236:239], v[240:241], off offset:512
.Lp2gB_mid:
	s_xor_b32 s99, s99, 1
	ds_read_b128 v[48:51], v75 offset:16384
	ds_read_b128 v[52:55], v75 offset:16400
	ds_read_b128 v[188:191], v75
	ds_read_b128 v[192:195], v75 offset:16
	ds_read_b128 v[196:199], v75 offset:1024
	ds_read_b128 v[200:203], v75 offset:1040
	ds_read_b128 v[204:207], v75 offset:2048
	ds_read_b128 v[210:213], v75 offset:2064
	ds_read_b128 v[214:217], v75 offset:3072
	ds_read_b128 v[218:221], v75 offset:3088
	s_waitcnt lgkmcnt(7)
	v_pk_fma_f32 v[50:51], v[84:85], v[190:191], v[50:51]
	v_pk_fma_f32 v[48:49], v[82:83], v[188:189], v[48:49]
	s_waitcnt lgkmcnt(6)
	v_pk_fma_f32 v[54:55], v[84:85], v[194:195], v[54:55]
	v_pk_fma_f32 v[52:53], v[82:83], v[192:193], v[52:53]
	s_waitcnt lgkmcnt(5)
	v_pk_fma_f32 v[50:51], v[28:29], v[198:199], v[50:51]
	v_pk_fma_f32 v[48:49], v[86:87], v[196:197], v[48:49]
	s_waitcnt lgkmcnt(4)
	v_pk_fma_f32 v[54:55], v[28:29], v[202:203], v[54:55]
	v_pk_fma_f32 v[52:53], v[86:87], v[200:201], v[52:53]
	s_waitcnt lgkmcnt(3)
	v_pk_fma_f32 v[50:51], v[90:91], v[206:207], v[50:51]
	v_pk_fma_f32 v[48:49], v[88:89], v[204:205], v[48:49]
	s_waitcnt lgkmcnt(2)
	v_pk_fma_f32 v[54:55], v[90:91], v[212:213], v[54:55]
	v_pk_fma_f32 v[52:53], v[88:89], v[210:211], v[52:53]
	s_waitcnt lgkmcnt(1)
	v_pk_fma_f32 v[132:133], v[30:31], v[216:217], v[50:51]
	v_pk_fma_f32 v[214:215], v[92:93], v[214:215], v[48:49]
	s_waitcnt lgkmcnt(0)
	v_pk_fma_f32 v[216:217], v[30:31], v[220:221], v[54:55]
	v_pk_fma_f32 v[218:219], v[92:93], v[218:219], v[52:53]
	ds_read_b128 v[48:51], v75 offset:4096
	ds_read_b128 v[52:55], v75 offset:4112
	ds_read_b128 v[188:191], v75 offset:5120
	ds_read_b128 v[192:195], v75 offset:5136
	ds_read_b128 v[196:199], v75 offset:6144
	ds_read_b128 v[200:203], v75 offset:6160
	ds_read_b128 v[204:207], v75 offset:7168
	ds_read_b128 v[210:213], v75 offset:7184
	s_waitcnt lgkmcnt(7)
	v_pk_fma_f32 v[50:51], v[96:97], v[50:51], v[132:133]
	v_pk_fma_f32 v[48:49], v[94:95], v[48:49], v[214:215]
	s_waitcnt lgkmcnt(6)
	v_pk_fma_f32 v[54:55], v[96:97], v[54:55], v[216:217]
	v_pk_fma_f32 v[52:53], v[94:95], v[52:53], v[218:219]
	s_waitcnt lgkmcnt(5)
	v_pk_fma_f32 v[50:51], v[24:25], v[190:191], v[50:51]
	v_pk_fma_f32 v[48:49], v[98:99], v[188:189], v[48:49]
	s_waitcnt lgkmcnt(4)
	v_pk_fma_f32 v[54:55], v[24:25], v[194:195], v[54:55]
	v_pk_fma_f32 v[52:53], v[98:99], v[192:193], v[52:53]
	s_waitcnt lgkmcnt(3)
	v_pk_fma_f32 v[50:51], v[102:103], v[198:199], v[50:51]
	v_pk_fma_f32 v[48:49], v[100:101], v[196:197], v[48:49]
	s_waitcnt lgkmcnt(2)
	v_pk_fma_f32 v[54:55], v[102:103], v[202:203], v[54:55]
	v_pk_fma_f32 v[52:53], v[100:101], v[200:201], v[52:53]
	s_waitcnt lgkmcnt(1)
	v_pk_fma_f32 v[132:133], v[26:27], v[206:207], v[50:51]
	v_pk_fma_f32 v[214:215], v[104:105], v[204:205], v[48:49]
	s_waitcnt lgkmcnt(0)
	v_pk_fma_f32 v[216:217], v[26:27], v[212:213], v[54:55]
	v_pk_fma_f32 v[218:219], v[104:105], v[210:211], v[52:53]
	ds_read_b128 v[48:51], v75 offset:8192
	ds_read_b128 v[52:55], v75 offset:8208
	ds_read_b128 v[188:191], v75 offset:9216
	ds_read_b128 v[192:195], v75 offset:9232
	ds_read_b128 v[196:199], v75 offset:10240
	ds_read_b128 v[200:203], v75 offset:10256
	ds_read_b128 v[204:207], v75 offset:11264
	ds_read_b128 v[210:213], v75 offset:11280
	s_waitcnt lgkmcnt(7)
	v_pk_fma_f32 v[50:51], v[108:109], v[50:51], v[132:133]
	v_pk_fma_f32 v[48:49], v[106:107], v[48:49], v[214:215]
	s_waitcnt lgkmcnt(6)
	v_pk_fma_f32 v[54:55], v[108:109], v[54:55], v[216:217]
	v_pk_fma_f32 v[52:53], v[106:107], v[52:53], v[218:219]
	s_waitcnt lgkmcnt(5)
	v_pk_fma_f32 v[50:51], v[20:21], v[190:191], v[50:51]
	v_pk_fma_f32 v[48:49], v[110:111], v[188:189], v[48:49]
	s_waitcnt lgkmcnt(4)
	v_pk_fma_f32 v[54:55], v[20:21], v[194:195], v[54:55]
	v_pk_fma_f32 v[52:53], v[110:111], v[192:193], v[52:53]
	s_waitcnt lgkmcnt(3)
	v_pk_fma_f32 v[50:51], v[114:115], v[198:199], v[50:51]
	v_pk_fma_f32 v[48:49], v[112:113], v[196:197], v[48:49]
	s_waitcnt lgkmcnt(2)
	v_pk_fma_f32 v[54:55], v[114:115], v[202:203], v[54:55]
	v_pk_fma_f32 v[52:53], v[112:113], v[200:201], v[52:53]
	s_waitcnt lgkmcnt(1)
	v_pk_fma_f32 v[132:133], v[22:23], v[206:207], v[50:51]
	v_pk_fma_f32 v[214:215], v[116:117], v[204:205], v[48:49]
	s_waitcnt lgkmcnt(0)
	v_pk_fma_f32 v[216:217], v[22:23], v[212:213], v[54:55]
	v_pk_fma_f32 v[218:219], v[116:117], v[210:211], v[52:53]
	ds_read_b128 v[48:51], v75 offset:12288
	ds_read_b128 v[52:55], v75 offset:12304
	ds_read_b128 v[188:191], v75 offset:13312
	ds_read_b128 v[192:195], v75 offset:13328
	ds_read_b128 v[196:199], v75 offset:14336
	ds_read_b128 v[200:203], v75 offset:14352
	ds_read_b128 v[204:207], v75 offset:15360
	ds_read_b128 v[210:213], v75 offset:15376
	s_waitcnt lgkmcnt(7)
	v_pk_fma_f32 v[48:49], v[118:119], v[48:49], v[214:215]
	s_waitcnt lgkmcnt(6)
	v_pk_fma_f32 v[54:55], v[120:121], v[54:55], v[216:217]
	s_waitcnt lgkmcnt(5)
	v_pk_fma_f32 v[48:49], v[122:123], v[188:189], v[48:49]
	s_waitcnt lgkmcnt(4)
	v_pk_fma_f32 v[54:55], v[124:125], v[194:195], v[54:55]
	s_waitcnt lgkmcnt(3)
	v_pk_fma_f32 v[48:49], v[126:127], v[196:197], v[48:49]
	v_pk_fma_f32 v[50:51], v[120:121], v[50:51], v[132:133]
	s_waitcnt lgkmcnt(2)
	v_pk_fma_f32 v[132:133], v[128:129], v[202:203], v[54:55]
	s_waitcnt lgkmcnt(1)
	v_pk_fma_f32 v[54:55], v[130:131], v[204:205], v[48:49]
	v_pk_fma_f32 v[50:51], v[124:125], v[190:191], v[50:51]
	v_mul_f32_e64 v75, |v54|, s80
	v_exp_f32_e32 v75, v75
	v_mul_f32_e64 v77, |v55|, s80
	v_exp_f32_e32 v77, v77
	v_pk_fma_f32 v[52:53], v[118:119], v[52:53], v[218:219]
	v_add_f32_e32 v75, 1.0, v75
	v_add_f32_e32 v77, 1.0, v77
	v_pk_fma_f32 v[52:53], v[122:123], v[192:193], v[52:53]
	v_log_f32_e32 v75, v75
	v_pk_fma_f32 v[50:51], v[128:129], v[198:199], v[50:51]
	v_pk_fma_f32 v[188:189], v[126:127], v[200:201], v[52:53]
	v_pk_fma_f32 v[52:53], v[18:19], v[206:207], v[50:51]
	v_mul_f32_e32 v190, 0x3f317217, v75
	v_fma_f32 v190, v75, s10, -v190
	v_fmac_f32_e32 v190, 0x3377d1cf, v75
	v_fmac_f32_e32 v190, 0x3f317217, v75
	v_mul_f32_e64 v79, |v52|, s80
	v_exp_f32_e32 v79, v79
	v_mov_b32_e32 v75, v190
	v_add_f32_e32 v79, 1.0, v79
	v_log_f32_e32 v77, v77
	s_waitcnt lgkmcnt(0)
	v_pk_fma_f32 v[48:49], v[18:19], v[212:213], v[132:133]
	v_mul_f32_e64 v132, |v53|, s80
	v_exp_f32_e32 v132, v132
	v_mul_f32_e32 v190, 0x3f317217, v77
	v_fma_f32 v190, v77, s10, -v190
	v_fmac_f32_e32 v190, 0x3377d1cf, v77
	v_fmac_f32_e32 v190, 0x3f317217, v77
	v_add_f32_e32 v132, 1.0, v132
	v_pk_fma_f32 v[50:51], v[130:131], v[210:211], v[188:189]
	v_mov_b32_e32 v77, v190
	v_mul_f32_e64 v133, |v50|, s80
	v_log_f32_e32 v79, v79
	v_exp_f32_e32 v133, v133
	v_mul_f32_e64 v187, |v51|, s80
	v_exp_f32_e32 v187, v187
	v_mul_f32_e32 v190, 0x3f317217, v79
	v_fma_f32 v190, v79, s10, -v190
	v_fmac_f32_e32 v190, 0x3377d1cf, v79
	v_fmac_f32_e32 v190, 0x3f317217, v79
	v_add_f32_e32 v133, 1.0, v133
	v_add_f32_e32 v187, 1.0, v187
	v_mov_b32_e32 v79, v190
	v_mul_f32_e64 v188, |v48|, s80
	v_log_f32_e32 v132, v132
	v_exp_f32_e32 v188, v188
	v_mul_f32_e64 v189, |v49|, s80
	v_exp_f32_e32 v189, v189
	v_mul_f32_e32 v190, 0x3f317217, v132
	v_fma_f32 v190, v132, s10, -v190
	v_fmac_f32_e32 v190, 0x3377d1cf, v132
	v_fmac_f32_e32 v190, 0x3f317217, v132
	v_add_f32_e32 v188, 1.0, v188
	v_add_f32_e32 v189, 1.0, v189
	v_mov_b32_e32 v132, v190
	v_min_f32_e32 v54, 0, v54
	v_log_f32_e32 v133, v133
	v_sub_f32_e32 v54, v54, v75
	v_min_f32_e32 v55, 0, v55
	v_mul_f32_e32 v75, 0x3d800000, v54
	v_mul_f32_e32 v190, 0x3f317217, v133
	v_fma_f32 v190, v133, s10, -v190
	v_fmac_f32_e32 v190, 0x3377d1cf, v133
	v_fmac_f32_e32 v190, 0x3f317217, v133
	v_sub_f32_e32 v55, v55, v77
	v_min_f32_e32 v52, 0, v52
	v_mov_b32_e32 v133, v190
	v_mul_f32_e32 v77, 0x3d800000, v55
	v_log_f32_e32 v187, v187
	v_sub_f32_e32 v52, v52, v79
	v_min_f32_e32 v53, 0, v53
	v_mov_b32_dpp v75, v75 row_shr:1 row_mask:0xf bank_mask:0xf bound_ctrl:1
	v_mul_f32_e32 v190, 0x3f317217, v187
	v_fma_f32 v190, v187, s10, -v190
	v_fmac_f32_e32 v190, 0x3377d1cf, v187
	v_fmac_f32_e32 v190, 0x3f317217, v187
	v_mul_f32_e32 v79, 0x3d800000, v52
	v_sub_f32_e32 v53, v53, v132
	v_mov_b32_e32 v187, v190
	v_min_f32_e32 v50, 0, v50
	v_log_f32_e32 v188, v188
	v_fmac_f32_e32 v75, 0x3d800000, v54
	v_mov_b32_dpp v54, v77 row_shr:1 row_mask:0xf bank_mask:0xf bound_ctrl:1
	v_mul_f32_e32 v132, 0x3d800000, v53
	v_mul_f32_e32 v190, 0x3f317217, v188
	v_fma_f32 v190, v188, s10, -v190
	v_fmac_f32_e32 v190, 0x3377d1cf, v188
	v_fmac_f32_e32 v190, 0x3f317217, v188
	v_sub_f32_e32 v50, v50, v133
	v_min_f32_e32 v51, 0, v51
	v_mov_b32_e32 v188, v190
	v_fmac_f32_e32 v54, 0x3d800000, v55
	v_log_f32_e32 v189, v189
	v_mov_b32_dpp v55, v79 row_shr:1 row_mask:0xf bank_mask:0xf bound_ctrl:1
	v_mul_f32_e32 v133, 0x3d800000, v50
	v_sub_f32_e32 v51, v51, v187
	v_mul_f32_e32 v190, 0x3f317217, v189
	v_fma_f32 v190, v189, s10, -v190
	v_fmac_f32_e32 v190, 0x3377d1cf, v189
	v_fmac_f32_e32 v190, 0x3f317217, v189
	v_min_f32_e32 v48, 0, v48
	v_fmac_f32_e32 v55, 0x3d800000, v52
	v_mov_b32_dpp v52, v132 row_shr:1 row_mask:0xf bank_mask:0xf bound_ctrl:1
	v_mov_b32_e32 v189, v190
	v_mul_f32_e32 v187, 0x3d800000, v51
	v_sub_f32_e32 v48, v48, v188
	v_min_f32_e32 v49, 0, v49
	v_fmac_f32_e32 v52, 0x3d800000, v53
	v_mov_b32_dpp v53, v133 row_shr:1 row_mask:0xf bank_mask:0xf bound_ctrl:1
	v_mul_f32_e32 v188, 0x3d800000, v48
	v_sub_f32_e32 v49, v49, v189
	v_fmac_f32_e32 v53, 0x3d800000, v50
	v_mov_b32_dpp v50, v187 row_shr:1 row_mask:0xf bank_mask:0xf bound_ctrl:1
	v_mul_f32_e32 v189, 0x3d800000, v49
	v_fmac_f32_e32 v50, 0x3d800000, v51
	v_mov_b32_dpp v51, v188 row_shr:1 row_mask:0xf bank_mask:0xf bound_ctrl:1
	v_fmac_f32_e32 v51, 0x3d800000, v48
	v_mov_b32_dpp v48, v189 row_shr:1 row_mask:0xf bank_mask:0xf bound_ctrl:1
	v_fmac_f32_e32 v48, 0x3d800000, v49
	v_add_f32_dpp v49, v75, v75 row_shr:2 row_mask:0xf bank_mask:0xf bound_ctrl:1
	v_add_f32_dpp v54, v54, v54 row_shr:2 row_mask:0xf bank_mask:0xf bound_ctrl:1
	s_nop 0
	v_add_f32_dpp v49, v49, v49 row_shr:4 row_mask:0xf bank_mask:0xf bound_ctrl:1
	v_add_f32_dpp v54, v54, v54 row_shr:4 row_mask:0xf bank_mask:0xf bound_ctrl:1
	v_add_f32_dpp v55, v55, v55 row_shr:2 row_mask:0xf bank_mask:0xf bound_ctrl:1
	v_add_f32_dpp v49, v49, v49 row_shr:8 row_mask:0xf bank_mask:0xf bound_ctrl:1
	v_add_f32_dpp v54, v54, v54 row_shr:8 row_mask:0xf bank_mask:0xf bound_ctrl:1
	v_add_f32_dpp v55, v55, v55 row_shr:4 row_mask:0xf bank_mask:0xf bound_ctrl:1
	v_add_f32_dpp v49, v49, v49 row_bcast:15 row_mask:0xa bank_mask:0xf
	v_add_f32_dpp v52, v52, v52 row_shr:2 row_mask:0xf bank_mask:0xf bound_ctrl:1
	v_add_f32_dpp v55, v55, v55 row_shr:8 row_mask:0xf bank_mask:0xf bound_ctrl:1
	v_add_f32_dpp v54, v54, v54 row_bcast:15 row_mask:0xa bank_mask:0xf
	v_max_f32_e32 v49, 0xc2a00000, v49
	v_add_f32_dpp v52, v52, v52 row_shr:4 row_mask:0xf bank_mask:0xf bound_ctrl:1
	v_mul_f32_e32 v49, 0x3fb8aa3b, v49
	v_add_f32_dpp v53, v53, v53 row_shr:2 row_mask:0xf bank_mask:0xf bound_ctrl:1
	v_add_f32_dpp v52, v52, v52 row_shr:8 row_mask:0xf bank_mask:0xf bound_ctrl:1
	v_add_f32_dpp v55, v55, v55 row_bcast:15 row_mask:0xa bank_mask:0xf
	v_exp_f32_e32 v132, v49
	v_max_f32_e32 v49, 0xc2a00000, v54
	v_add_f32_dpp v53, v53, v53 row_shr:4 row_mask:0xf bank_mask:0xf bound_ctrl:1
	v_mul_f32_e32 v49, 0x3fb8aa3b, v49
	v_add_f32_dpp v50, v50, v50 row_shr:2 row_mask:0xf bank_mask:0xf bound_ctrl:1
	v_add_f32_dpp v53, v53, v53 row_shr:8 row_mask:0xf bank_mask:0xf bound_ctrl:1
	v_add_f32_dpp v52, v52, v52 row_bcast:15 row_mask:0xa bank_mask:0xf
	v_exp_f32_e32 v133, v49
	v_max_f32_e32 v49, 0xc2a00000, v55
	v_add_f32_dpp v50, v50, v50 row_shr:4 row_mask:0xf bank_mask:0xf bound_ctrl:1
	v_mul_f32_e32 v49, 0x3fb8aa3b, v49
	v_add_f32_dpp v51, v51, v51 row_shr:2 row_mask:0xf bank_mask:0xf bound_ctrl:1
	v_add_f32_dpp v50, v50, v50 row_shr:8 row_mask:0xf bank_mask:0xf bound_ctrl:1
	v_add_f32_dpp v53, v53, v53 row_bcast:15 row_mask:0xa bank_mask:0xf
	v_exp_f32_e32 v188, v49
	v_max_f32_e32 v49, 0xc2a00000, v52
	v_add_f32_dpp v51, v51, v51 row_shr:4 row_mask:0xf bank_mask:0xf bound_ctrl:1
	v_mul_f32_e32 v49, 0x3fb8aa3b, v49
	v_add_f32_dpp v48, v48, v48 row_shr:2 row_mask:0xf bank_mask:0xf bound_ctrl:1
	v_add_f32_dpp v51, v51, v51 row_shr:8 row_mask:0xf bank_mask:0xf bound_ctrl:1
	v_add_f32_dpp v50, v50, v50 row_bcast:15 row_mask:0xa bank_mask:0xf
	v_exp_f32_e32 v189, v49
	v_max_f32_e32 v49, 0xc2a00000, v53
	v_add_f32_dpp v48, v48, v48 row_shr:4 row_mask:0xf bank_mask:0xf bound_ctrl:1
	v_mul_f32_e32 v49, 0x3fb8aa3b, v49
	s_nop 0
	v_add_f32_dpp v48, v48, v48 row_shr:8 row_mask:0xf bank_mask:0xf bound_ctrl:1
	v_add_f32_dpp v51, v51, v51 row_bcast:15 row_mask:0xa bank_mask:0xf
	v_exp_f32_e32 v190, v49
	v_max_f32_e32 v49, 0xc2a00000, v50
	v_mul_f32_e32 v49, 0x3fb8aa3b, v49
	v_add_f32_dpp v48, v48, v48 row_bcast:15 row_mask:0xa bank_mask:0xf
	v_exp_f32_e32 v191, v49
	v_max_f32_e32 v49, 0xc2a00000, v51
	v_max_f32_e32 v48, 0xc2a00000, v48
	v_rcp_f32_e32 v196, v188
	v_rcp_f32_e32 v197, v189
	v_mul_f32_e32 v49, 0x3fb8aa3b, v49
	v_mul_f32_e32 v48, 0x3fb8aa3b, v48
	v_lshlrev_b32_e32 v202, 16, v44
	v_and_b32_e32 v203, 0xffff0000, v44
	v_exp_f32_e32 v192, v49
	v_exp_f32_e32 v193, v48
	ds_bpermute_b32 v48, v244, v132
	ds_bpermute_b32 v49, v244, v133
	ds_bpermute_b32 v50, v244, v188
	ds_bpermute_b32 v51, v244, v189
	ds_bpermute_b32 v52, v244, v190
	ds_bpermute_b32 v53, v244, v191
	ds_bpermute_b32 v54, v244, v192
	ds_bpermute_b32 v55, v244, v193
	v_pk_mul_f32 v[202:203], v[202:203], s[90:91] op_sel_hi:[1,0]
	v_lshlrev_b32_e32 v44, 16, v45
	v_and_b32_e32 v45, 0xffff0000, v45
	v_rcp_f32_e32 v194, v132
	v_rcp_f32_e32 v195, v133
	v_rcp_f32_e32 v198, v190
	v_rcp_f32_e32 v199, v191
	v_pk_mul_f32 v[132:133], v[202:203], v[132:133]
	v_lshlrev_b32_e32 v202, 16, v40
	v_and_b32_e32 v203, 0xffff0000, v40
	v_pk_mul_f32 v[44:45], v[44:45], s[90:91] op_sel_hi:[1,0]
	v_lshlrev_b32_e32 v40, 16, v41
	v_and_b32_e32 v41, 0xffff0000, v41
	v_pk_mul_f32 v[44:45], v[44:45], v[188:189]
	v_pk_mul_f32 v[188:189], v[196:197], v[40:41]
	v_lshlrev_b32_e32 v40, 16, v46
	v_and_b32_e32 v41, 0xffff0000, v46
	v_pk_mul_f32 v[40:41], v[40:41], s[90:91] op_sel_hi:[1,0]
	v_rcp_f32_e32 v200, v192
	v_rcp_f32_e32 v201, v193
	v_pk_mul_f32 v[190:191], v[40:41], v[190:191]
	v_lshlrev_b32_e32 v40, 16, v42
	v_and_b32_e32 v41, 0xffff0000, v42
	v_pk_mul_f32 v[196:197], v[198:199], v[40:41]
	v_lshlrev_b32_e32 v40, 16, v47
	v_and_b32_e32 v41, 0xffff0000, v47
	v_pk_mul_f32 v[40:41], v[40:41], s[90:91] op_sel_hi:[1,0]
	v_pk_mul_f32 v[46:47], v[40:41], v[192:193]
	v_lshlrev_b32_e32 v40, 16, v43
	v_and_b32_e32 v41, 0xffff0000, v43
	v_pk_mul_f32 v[194:195], v[194:195], v[202:203]
	v_pk_mul_f32 v[192:193], v[200:201], v[40:41]
	v_cvt_pk_bf16_f32 v41, v44, v45
	v_cvt_pk_bf16_f32 v43, v46, v47
	v_cvt_pk_bf16_f32 v44, v194, v195
	v_cvt_pk_bf16_f32 v45, v188, v189
	v_cvt_pk_bf16_f32 v46, v196, v197
	v_cvt_pk_bf16_f32 v47, v192, v193
	v_cvt_pk_bf16_f32 v40, v132, v133
	v_cvt_pk_bf16_f32 v42, v190, v191
	s_nop 1
	v_mfma_f32_32x32x16_bf16 v[2:17], v[44:47], v[40:43], v[2:17]
	s_waitcnt lgkmcnt(0)
	v_mul_f32_e32 v75, v194, v48
	v_mul_f32_e32 v77, v195, v49
	v_xor_b32_e32 v132, v71, v168
	v_mul_f32_e32 v79, v188, v50
	v_mul_f32_e32 v187, v189, v51
	v_lshl_add_u32 v132, v132, 4, v167
	v_cvt_pk_bf16_f32 v75, v75, v77
	v_mul_f32_e32 v198, v196, v52
	v_mul_f32_e32 v199, v197, v53
	ds_write_b128 v132, v[40:43] offset:20480
	ds_write_b16 v73, v75
	ds_write_b16_d16_hi v73, v75 offset:64
	v_cvt_pk_bf16_f32 v75, v79, v187
	v_mul_f32_e32 v200, v192, v54
	v_mul_f32_e32 v201, v193, v55
	ds_write_b16 v73, v75 offset:128
	ds_write_b16_d16_hi v73, v75 offset:192
	v_cvt_pk_bf16_f32 v75, v198, v199
	ds_write_b16 v73, v75 offset:256
	ds_write_b16_d16_hi v73, v75 offset:320
	v_cvt_pk_bf16_f32 v75, v200, v201
	ds_write_b16 v73, v75 offset:384
	ds_write_b16_d16_hi v73, v75 offset:448
	s_and_saveexec_b64 s[0:1], s[4:5]
	s_cbranch_execz .LBB0_631
	v_add_u32_e32 v40, s41, v183
	ds_write_b128 v40, v[48:51]
	ds_write_b128 v40, v[52:55] offset:16
	s_branch .LBB0_631
